# speedup vs baseline: 1.0155x; 1.0155x over previous
; DEV void phase_gemm(const u16* A, const u16* Bt, u16* C, int ntiles, int N, int K, unsigned char* smem, int epi, const GateEpi& ge) {
;   const int nN = N >> 8;
;   const int lb = (blockIdx.x & 7) * (gridDim.x >> 3) + (blockIdx.x >> 3);
;   const int nig = 8 * nN;
;   int gid = 0, rem = lb;
;   for (int t = lb; t < ntiles; t += gridDim.x) {
;     while (rem >= nig) { rem -= nig; ++gid; }
;     const int pm = gid * 8 + (rem & 7), pn = rem >> 3;
.LBB0_626:
	s_cmp_ge_i32 s65, s43
	s_cbranch_scc1 .LBB0_818
	s_lshr_b32 s45, s18, 6
	s_xor_b64 s[2:3], s[6:7], -1
	s_lshr_b32 s42, s44, 4
	s_lshl_b64 s[16:17], s[18:19], 8
	s_add_i32 s45, s45, -2
	v_mul_u32_u24_e64 v131, s44, 13
	s_mov_b32 s46, 0
	s_mov_b32 s47, s65
	s_mov_b32 s48, s65
	s_branch .LBB0_629

; #define STAGE(P, q) do { GLDS16(q[0], (unsigned char*)(P) + wid * 1024); GLDS16(q[1], (unsigned char*)(P) + wid * 1024 + 8192); \
;     q[0] += 128; q[1] += 128; asm volatile("" : "+v"(q[0]), "+v"(q[1])); } while (0)
; #define WAIT_V(n) asm volatile("s_waitcnt vmcnt(" #n ")" ::: "memory")
; #define WAIT_L(n) asm volatile("s_waitcnt lgkmcnt(" #n ")" ::: "memory")
; #define BAR __builtin_amdgcn_s_barrier()
; DEV void gemm_tile(const u16* __restrict__ A, const u16* __restrict__ Bt, u16* __restrict__ C, int N, int K,
;                    int brow, int bcol, unsigned char* smem, int epi, const GateEpi& ge) {
;     ...
;   {
;     int r, c;
;     stage_rc1(tid * 16, r, c);
;     size_t o0 = ((size_t)r * K + c) * 2;
;     stage_rc1(tid * 16 + 8192, r, c);
;     size_t o1 = ((size_t)r * K + c) * 2;
;     const unsigned char* a0 = (const unsigned char*)(A + (size_t)brow * K);
;     const unsigned char* b0 = (const unsigned char*)(Bt + (size_t)bcol * K);
;     const size_t hoff = (size_t)128 * K * 2;
;     qA0[0] = a0 + o0; qA0[1] = a0 + o1; qA1[0] = a0 + hoff + o0; qA1[1] = a0 + hoff + o1;
;     qB0[0] = b0 + o0; qB0[1] = b0 + o1; qB1[0] = b0 + hoff + o0; qB1[1] = b0 + hoff + o1;
;   }
;     ...
;   f32x4 acc[2][2][4][2];
; #pragma unroll
;   for (int a = 0; a < 2; ++a)
; #pragma unroll
;     for (int b = 0; b < 2; ++b)
; #pragma unroll
;       for (int m = 0; m < 4; ++m)
; #pragma unroll
;         for (int n = 0; n < 2; ++n) acc[a][b][m][n] = (f32x4){0.f, 0.f, 0.f, 0.f};
;   bf16x8 At[4][2], B0[2][2], B1[2][2];
;   const int nt = K / 64;
;   WAIT_L(0);
;   __syncthreads();
;   STAGE(SB(0, 0), qB0); STAGE(SA(0, 0), qA0);
;   STAGE(SB(0, 1), qB1); STAGE(SA(0, 1), qA1);
;   if (wr == 1) BAR;
;   WAIT_V(4); BAR;
;   STAGE(SB(1, 0), qB0); STAGE(SA(1, 0), qA0); STAGE(SB(1, 1), qB1);
;   WAIT_V(6); BAR;
; DEV void phase_gemm(const u16* A, const u16* Bt, u16* C, int ntiles, int N, int K, unsigned char* smem, int epi, const GateEpi& ge) {
;     ...
;   const int lb = (blockIdx.x & 7) * (gridDim.x >> 3) + (blockIdx.x >> 3);
;   const int nig = 8 * nN;
;   int gid = 0, rem = lb;
;   for (int t = lb; t < ntiles; t += gridDim.x) {
;     while (rem >= nig) { rem -= nig; ++gid; }
;     const int pm = gid * 8 + (rem & 7), pn = rem >> 3;
;     gemm_tile(A, Bt, C, N, K, pm * 256, pn * 256, smem, epi, ge);
.LBB0_631:
	s_lshl_b32 s0, s46, 12
	s_lshr_b32 s1, s47, 5
	s_and_b32 s1, s1, 1
	s_lshl_b32 s1, s1, 11
	s_or_b32 s0, s0, s1
	s_and_b32 s1, s47, 7
	s_lshl_b32 s1, s1, 8
	s_or_b32 s49, s0, s1
	s_lshr_b32 s0, s47, 6
	s_lshl_b32 s0, s0, 2
	s_bfe_u32 s1, s47, 0x20003
	s_or_b32 s0, s0, s1
	s_lshl_b32 s92, s0, 8
	s_mov_b32 s1, s49
	v_readfirstlane_b32 s0, v160
	s_andn2_b32 s0, s0, 63
	s_ashr_i32 s1, s1, 31
	v_or_b32_e32 v12, s0, v161
	s_mul_i32 s1, s1, s18
	v_lshlrev_b32_e32 v4, 4, v12
	v_and_b32_e32 v0, 32, v12
	v_ashrrev_i32_e32 v1, 3, v12
	v_lshrrev_b32_e32 v5, 2, v12
	v_bitop3_b32 v0, v4, v0, 48 bitop3:0x6c
	v_bfi_b32 v2, 15, v5, v1
	v_lshrrev_b32_e32 v3, 1, v12
	v_lshrrev_b32_e32 v0, 1, v0
	v_and_or_b32 v6, v3, 32, v0
	v_ashrrev_i32_e32 v3, 31, v1
	v_mad_u64_u32 v[0:1], s[4:5], v2, s18, 0
	v_mov_b32_e32 v2, v1
	v_mad_u64_u32 v[2:3], s[4:5], v3, s18, v[2:3]
	v_mov_b32_e32 v1, v2
	v_add_u32_e32 v2, 0x2000, v4
	v_ashrrev_i32_e32 v2, 7, v2
	v_bfi_b32 v3, -16, v2, v5
	v_ashrrev_i32_e32 v5, 31, v2
	v_mad_u64_u32 v[2:3], s[4:5], v3, s18, 0
	v_mov_b32_e32 v4, v3
	v_mad_u64_u32 v[4:5], s[4:5], v5, s18, v[4:5]
	s_mul_hi_u32 s4, s49, s18
	v_readfirstlane_b32 s0, v12
	s_add_i32 s5, s4, s1
	s_mul_i32 s4, s49, s18
	s_ashr_i32 s34, s0, 8
	s_lshl_b64 s[4:5], s[4:5], 1
	s_add_u32 s4, s10, s4
	s_addc_u32 s5, s11, s5
	s_ashr_i32 s93, s92, 31
	s_mul_i32 s1, s93, s18
	s_mul_hi_u32 s6, s92, s18
	s_add_i32 s7, s6, s1
	s_mul_i32 s6, s92, s18
	s_lshl_b64 s[6:7], s[6:7], 1
	s_add_u32 s6, s12, s6
	s_addc_u32 s7, s13, s7
	s_add_u32 s50, s4, s16
	s_addc_u32 s51, s5, s17
	s_add_u32 s52, s6, s16
	v_or_b32_e32 v0, v0, v6
	v_or_b32_e32 v2, v2, v6
	v_mov_b32_e32 v3, v4
	s_addc_u32 s53, s7, s17
	s_ashr_i32 s28, s0, 6
	v_lshlrev_b64 v[0:1], 1, v[0:1]
	v_lshlrev_b64 v[2:3], 1, v[2:3]
	s_lshl_b32 s1, s28, 10
	v_lshl_add_u64 v[4:5], s[4:5], 0, v[0:1]
	s_waitcnt vmcnt(0)
	v_lshl_add_u64 v[16:17], s[4:5], 0, v[2:3]
	s_add_i32 s4, s1, 0x10000
	v_lshl_add_u64 v[6:7], s[6:7], 0, v[0:1]
	s_mov_b32 m0, s4
	s_add_i32 s5, s1, 0x12000
	v_lshl_add_u64 v[10:11], s[6:7], 0, v[2:3]
	s_waitcnt lgkmcnt(0)
	s_waitcnt lgkmcnt(0)
	s_barrier
	global_load_lds_dwordx4 v[6:7], off
	s_mov_b32 m0, s5
	v_lshl_add_u64 v[8:9], v[6:7], 0, s[8:9]
	global_load_lds_dwordx4 v[10:11], off
	v_lshl_add_u64 v[10:11], v[10:11], 0, s[8:9]
	s_mov_b32 m0, s1
	s_add_i32 s6, s1, 0x2000
	global_load_lds_dwordx4 v[4:5], off
	s_mov_b32 m0, s6
	s_add_i32 s7, s1, 0x14000
	v_lshl_add_u64 v[14:15], s[50:51], 0, v[0:1]
	v_lshl_add_u64 v[0:1], s[52:53], 0, v[0:1]
	global_load_lds_dwordx4 v[16:17], off
	v_lshl_add_u64 v[4:5], v[4:5], 0, s[8:9]
	v_lshl_add_u64 v[6:7], v[16:17], 0, s[8:9]
	s_mov_b32 m0, s7
	s_add_i32 s35, s1, 0x16000
	v_lshl_add_u64 v[18:19], s[50:51], 0, v[2:3]
	v_lshl_add_u64 v[2:3], s[52:53], 0, v[2:3]
	global_load_lds_dwordx4 v[0:1], off
	s_mov_b32 m0, s35
	s_add_i32 s41, s1, 0x4000
	global_load_lds_dwordx4 v[2:3], off
	v_lshl_add_u64 v[0:1], v[0:1], 0, s[8:9]
	v_lshl_add_u64 v[2:3], v[2:3], 0, s[8:9]
	s_mov_b32 m0, s41
	s_add_i32 vcc_lo, s1, 0x6000
	global_load_lds_dwordx4 v[14:15], off
	s_mov_b32 m0, vcc_lo
	v_lshl_add_u64 v[132:133], v[14:15], 0, s[8:9]
	global_load_lds_dwordx4 v[18:19], off
	v_lshl_add_u64 v[134:135], v[18:19], 0, s[8:9]
	s_cmp_lg_u32 s34, 1
	s_cbranch_scc1 .LBB0_633
	s_barrier

; #define STAGE(P, q) do { GLDS16(q[0], (unsigned char*)(P) + wid * 1024); GLDS16(q[1], (unsigned char*)(P) + wid * 1024 + 8192); \
;     q[0] += 128; q[1] += 128; asm volatile("" : "+v"(q[0]), "+v"(q[1])); } while (0)
; #define LDA(dst, b, h) _Pragma("unroll") for (int m = 0; m < 4; ++m) _Pragma("unroll") for (int k = 0; k < 2; ++k) \
;     dst[m][k] = *(const bf16x8*)((const unsigned char*)SA(b, h) + lds_byte1(wr * 64 + m * 16 + fr, k * 32 + fq * 8))
; #define LDB(dst, b, h) _Pragma("unroll") for (int n = 0; n < 2; ++n) _Pragma("unroll") for (int k = 0; k < 2; ++k) \
;     dst[n][k] = *(const bf16x8*)((const unsigned char*)SB(b, h) + lds_byte1(wc * 32 + n * 16 + fr, k * 32 + fq * 8))
; #define MMA(ai, bj, At_, Bt_) do { __builtin_amdgcn_s_setprio(1); \
;     _Pragma("unroll") for (int m = 0; m < 4; ++m) _Pragma("unroll") for (int n = 0; n < 2; ++n) _Pragma("unroll") for (int k = 0; k < 2; ++k) \
;       acc[ai][bj][m][n] = mfma16(At_[m][k], Bt_[n][k], acc[ai][bj][m][n]); \
;     __builtin_amdgcn_s_setprio(0); } while (0)
; #define WAIT_V(n) asm volatile("s_waitcnt vmcnt(" #n ")" ::: "memory")
; #define WAIT_L(n) asm volatile("s_waitcnt lgkmcnt(" #n ")" ::: "memory")
; #define BAR __builtin_amdgcn_s_barrier()
; #define SCHED __builtin_amdgcn_sched_barrier(0)
; DEV void gemm_tile(const u16* __restrict__ A, const u16* __restrict__ Bt, u16* __restrict__ C, int N, int K,
;                    int brow, int bcol, unsigned char* smem, int epi, const GateEpi& ge) {
;     ...
;   for (int t = 0; t < nt - 2; t += 2) {
;     LDB(B0, 0, 0); SCHED; LDA(At, 0, 0); STAGE(SA(1, 1), qA1);
;     WAIT_L(8); BAR; WAIT_L(0); MMA(0, 0, At, B0); BAR; SCHED;
;     LDB(B1, 0, 1); STAGE(SB(0, 0), qB0);
;     BAR; WAIT_L(0); MMA(0, 1, At, B1); BAR;
;     LDA(At, 0, 1); STAGE(SA(0, 0), qA0);
;     BAR; WAIT_L(0); MMA(1, 0, At, B0); BAR; SCHED;
;     STAGE(SB(0, 1), qB1);
;     WAIT_V(6); BAR; MMA(1, 1, At, B1); BAR;
.LBB0_634:
	ds_read_b128 v[156:159], v152
	ds_read_b128 v[180:183], v152 offset:1024
	ds_read_b128 v[184:187], v152 offset:256
	ds_read_b128 v[188:191], v152 offset:1280
	s_mov_b32 m0, s56
	v_add_u32_e32 v153, s53, v151
	v_add_u32_e32 v154, s54, v151
	v_add_u32_e32 v155, s55, v151
	ds_read_b128 v[192:195], v128
	ds_read_b128 v[196:199], v128 offset:1024
	ds_read_b128 v[200:203], v153
	ds_read_b128 v[204:207], v153 offset:1024
	ds_read_b128 v[208:211], v154
	ds_read_b128 v[212:215], v154 offset:1024
	ds_read_b128 v[216:219], v155
	ds_read_b128 v[220:223], v155 offset:1024
	global_load_lds_dwordx4 v[132:133], off
	s_mov_b32 m0, s52
	v_lshl_add_u64 v[236:237], v[132:133], 0, s[8:9]
	global_load_lds_dwordx4 v[134:135], off
	v_lshl_add_u64 v[238:239], v[134:135], 0, s[8:9]
	s_waitcnt lgkmcnt(8)
	s_barrier
	s_waitcnt lgkmcnt(0)
	s_setprio 1
	s_waitcnt lgkmcnt(0)
	v_mfma_f32_16x16x32_bf16 v[124:127], v[156:159], v[192:195], v[124:127]
	v_mfma_f32_16x16x32_bf16 v[120:123], v[184:187], v[192:195], v[120:123]
	v_mfma_f32_16x16x32_bf16 v[116:119], v[156:159], v[200:203], v[116:119]
	v_mfma_f32_16x16x32_bf16 v[112:115], v[184:187], v[200:203], v[112:115]
	v_mfma_f32_16x16x32_bf16 v[108:111], v[156:159], v[208:211], v[108:111]
	v_mfma_f32_16x16x32_bf16 v[104:107], v[184:187], v[208:211], v[104:107]
	v_mfma_f32_16x16x32_bf16 v[100:103], v[156:159], v[216:219], v[100:103]
	v_mfma_f32_16x16x32_bf16 v[96:99], v[184:187], v[216:219], v[96:99]
	v_mfma_f32_16x16x32_bf16 v[124:127], v[180:183], v[196:199], v[124:127]
	v_mfma_f32_16x16x32_bf16 v[120:123], v[188:191], v[196:199], v[120:123]
	v_mfma_f32_16x16x32_bf16 v[116:119], v[180:183], v[204:207], v[116:119]
	v_mfma_f32_16x16x32_bf16 v[112:115], v[188:191], v[204:207], v[112:115]
	v_mfma_f32_16x16x32_bf16 v[108:111], v[180:183], v[212:215], v[108:111]
	v_mfma_f32_16x16x32_bf16 v[104:107], v[188:191], v[212:215], v[104:107]
	v_mfma_f32_16x16x32_bf16 v[100:103], v[180:183], v[220:223], v[100:103]
	v_mfma_f32_16x16x32_bf16 v[96:99], v[188:191], v[220:223], v[96:99]
	s_setprio 0
	s_barrier
	s_mov_b32 m0, s4
	ds_read_b128 v[132:135], v150
	ds_read_b128 v[224:227], v150 offset:1024
	ds_read_b128 v[228:231], v150 offset:256
	ds_read_b128 v[232:235], v150 offset:1280
	global_load_lds_dwordx4 v[136:137], off
	s_mov_b32 m0, s5
	v_lshl_add_u64 v[240:241], v[136:137], 0, s[8:9]
	global_load_lds_dwordx4 v[138:139], off
	v_lshl_add_u64 v[242:243], v[138:139], 0, s[8:9]
	s_barrier
	s_waitcnt lgkmcnt(0)
	s_setprio 1
	s_waitcnt lgkmcnt(0)
	v_mfma_f32_16x16x32_bf16 v[84:87], v[132:135], v[192:195], v[84:87]
	v_mfma_f32_16x16x32_bf16 v[68:71], v[228:231], v[192:195], v[68:71]
	v_mfma_f32_16x16x32_bf16 v[52:55], v[132:135], v[200:203], v[52:55]
	v_mfma_f32_16x16x32_bf16 v[48:51], v[228:231], v[200:203], v[48:51]
	v_mfma_f32_16x16x32_bf16 v[44:47], v[132:135], v[208:211], v[44:47]
	v_mfma_f32_16x16x32_bf16 v[40:43], v[228:231], v[208:211], v[40:43]
	v_mfma_f32_16x16x32_bf16 v[36:39], v[132:135], v[216:219], v[36:39]
	v_mfma_f32_16x16x32_bf16 v[32:35], v[228:231], v[216:219], v[32:35]
	v_mfma_f32_16x16x32_bf16 v[84:87], v[224:227], v[196:199], v[84:87]
	v_mfma_f32_16x16x32_bf16 v[68:71], v[232:235], v[196:199], v[68:71]
	v_mfma_f32_16x16x32_bf16 v[52:55], v[224:227], v[204:207], v[52:55]
	v_mfma_f32_16x16x32_bf16 v[48:51], v[232:235], v[204:207], v[48:51]
	v_mfma_f32_16x16x32_bf16 v[44:47], v[224:227], v[212:215], v[44:47]
	v_mfma_f32_16x16x32_bf16 v[40:43], v[232:235], v[212:215], v[40:43]
	v_mfma_f32_16x16x32_bf16 v[36:39], v[224:227], v[220:223], v[36:39]
	v_mfma_f32_16x16x32_bf16 v[32:35], v[232:235], v[220:223], v[32:35]
	s_setprio 0
	s_mov_b32 m0, s1
	s_barrier
	ds_read_b128 v[136:139], v128 offset:16384
	ds_read_b128 v[192:195], v128 offset:17408
	ds_read_b128 v[196:199], v153 offset:16384
	ds_read_b128 v[200:203], v153 offset:17408
	ds_read_b128 v[204:207], v154 offset:16384
	ds_read_b128 v[208:211], v154 offset:17408
	ds_read_b128 v[212:215], v155 offset:16384
	ds_read_b128 v[216:219], v155 offset:17408
	global_load_lds_dwordx4 v[140:141], off
	s_mov_b32 m0, s6
	v_lshl_add_u64 v[244:245], v[140:141], 0, s[8:9]
	global_load_lds_dwordx4 v[142:143], off
	v_lshl_add_u64 v[246:247], v[142:143], 0, s[8:9]
	s_barrier
	s_waitcnt lgkmcnt(0)
	s_setprio 1
	s_waitcnt lgkmcnt(0)
	v_mfma_f32_16x16x32_bf16 v[28:31], v[156:159], v[136:139], v[28:31]
	v_mfma_f32_16x16x32_bf16 v[24:27], v[184:187], v[136:139], v[24:27]
	v_mfma_f32_16x16x32_bf16 v[20:23], v[156:159], v[196:199], v[20:23]
	v_mfma_f32_16x16x32_bf16 v[16:19], v[184:187], v[196:199], v[16:19]
	v_mfma_f32_16x16x32_bf16 v[12:15], v[156:159], v[204:207], v[12:15]
	v_mfma_f32_16x16x32_bf16 v[8:11], v[184:187], v[204:207], v[8:11]
	v_mfma_f32_16x16x32_bf16 v[4:7], v[156:159], v[212:215], v[4:7]
	v_mfma_f32_16x16x32_bf16 v[0:3], v[184:187], v[212:215], v[0:3]
	v_mfma_f32_16x16x32_bf16 v[28:31], v[180:183], v[192:195], v[28:31]
	v_mfma_f32_16x16x32_bf16 v[24:27], v[188:191], v[192:195], v[24:27]
	v_mfma_f32_16x16x32_bf16 v[20:23], v[180:183], v[200:203], v[20:23]
	v_mfma_f32_16x16x32_bf16 v[16:19], v[188:191], v[200:203], v[16:19]
	v_mfma_f32_16x16x32_bf16 v[12:15], v[180:183], v[208:211], v[12:15]
	v_mfma_f32_16x16x32_bf16 v[8:11], v[188:191], v[208:211], v[8:11]
	v_mfma_f32_16x16x32_bf16 v[4:7], v[180:183], v[216:219], v[4:7]
	v_mfma_f32_16x16x32_bf16 v[0:3], v[188:191], v[216:219], v[0:3]
	s_setprio 0
	s_barrier
	s_mov_b32 m0, s7
	v_lshl_add_u64 v[248:249], v[144:145], 0, s[8:9]
	global_load_lds_dwordx4 v[144:145], off
	s_mov_b32 m0, s35
	v_lshl_add_u64 v[250:251], v[146:147], 0, s[8:9]
	global_load_lds_dwordx4 v[146:147], off
	s_waitcnt vmcnt(6)
	s_barrier
; #define STAGE(P, q) do { GLDS16(q[0], (unsigned char*)(P) + wid * 1024); GLDS16(q[1], (unsigned char*)(P) + wid * 1024 + 8192); \
;     q[0] += 128; q[1] += 128; asm volatile("" : "+v"(q[0]), "+v"(q[1])); } while (0)
; #define LDA(dst, b, h) _Pragma("unroll") for (int m = 0; m < 4; ++m) _Pragma("unroll") for (int k = 0; k < 2; ++k) \
;     dst[m][k] = *(const bf16x8*)((const unsigned char*)SA(b, h) + lds_byte1(wr * 64 + m * 16 + fr, k * 32 + fq * 8))
; #define LDB(dst, b, h) _Pragma("unroll") for (int n = 0; n < 2; ++n) _Pragma("unroll") for (int k = 0; k < 2; ++k) \
;     dst[n][k] = *(const bf16x8*)((const unsigned char*)SB(b, h) + lds_byte1(wc * 32 + n * 16 + fr, k * 32 + fq * 8))
; #define MMA(ai, bj, At_, Bt_) do { __builtin_amdgcn_s_setprio(1); \
;     _Pragma("unroll") for (int m = 0; m < 4; ++m) _Pragma("unroll") for (int n = 0; n < 2; ++n) _Pragma("unroll") for (int k = 0; k < 2; ++k) \
;       acc[ai][bj][m][n] = mfma16(At_[m][k], Bt_[n][k], acc[ai][bj][m][n]); \
;     __builtin_amdgcn_s_setprio(0); } while (0)
; #define WAIT_V(n) asm volatile("s_waitcnt vmcnt(" #n ")" ::: "memory")
; #define WAIT_L(n) asm volatile("s_waitcnt lgkmcnt(" #n ")" ::: "memory")
; #define BAR __builtin_amdgcn_s_barrier()
; #define SCHED __builtin_amdgcn_sched_barrier(0)
; DEV void gemm_tile(const u16* __restrict__ A, const u16* __restrict__ Bt, u16* __restrict__ C, int N, int K,
;                    int brow, int bcol, unsigned char* smem, int epi, const GateEpi& ge) {
;     ...
;     WAIT_V(6); BAR; MMA(1, 1, At, B1); BAR;
;     LDB(B0, 1, 0); SCHED; LDA(At, 1, 0); STAGE(SA(0, 1), qA1);
;     WAIT_L(8); BAR; WAIT_L(0); MMA(0, 0, At, B0); BAR; SCHED;
;     LDB(B1, 1, 1); STAGE(SB(1, 0), qB0);
;     BAR; WAIT_L(0); MMA(0, 1, At, B1); BAR;
;     LDA(At, 1, 1); STAGE(SA(1, 0), qA0);
;     BAR; WAIT_L(0); MMA(1, 0, At, B0); BAR; SCHED;
	s_setprio 1
	v_mfma_f32_16x16x32_bf16 v[56:59], v[132:135], v[136:139], v[56:59]
	v_mfma_f32_16x16x32_bf16 v[60:63], v[228:231], v[136:139], v[60:63]
	v_mfma_f32_16x16x32_bf16 v[64:67], v[132:135], v[196:199], v[64:67]
	v_mfma_f32_16x16x32_bf16 v[72:75], v[228:231], v[196:199], v[72:75]
	v_mfma_f32_16x16x32_bf16 v[76:79], v[132:135], v[204:207], v[76:79]
	v_mfma_f32_16x16x32_bf16 v[80:83], v[228:231], v[204:207], v[80:83]
	v_mfma_f32_16x16x32_bf16 v[88:91], v[132:135], v[212:215], v[88:91]
	v_mfma_f32_16x16x32_bf16 v[92:95], v[228:231], v[212:215], v[92:95]
	v_mfma_f32_16x16x32_bf16 v[56:59], v[224:227], v[192:195], v[56:59]
	v_mfma_f32_16x16x32_bf16 v[60:63], v[232:235], v[192:195], v[60:63]
	v_mfma_f32_16x16x32_bf16 v[64:67], v[224:227], v[200:203], v[64:67]
	v_mfma_f32_16x16x32_bf16 v[72:75], v[232:235], v[200:203], v[72:75]
	v_mfma_f32_16x16x32_bf16 v[76:79], v[224:227], v[208:211], v[76:79]
	v_mfma_f32_16x16x32_bf16 v[80:83], v[232:235], v[208:211], v[80:83]
	v_mfma_f32_16x16x32_bf16 v[88:91], v[224:227], v[216:219], v[88:91]
	v_mfma_f32_16x16x32_bf16 v[92:95], v[232:235], v[216:219], v[92:95]
	s_setprio 0
	s_barrier
	ds_read_b128 v[144:147], v149
	ds_read_b128 v[156:159], v149 offset:1024
	ds_read_b128 v[180:183], v149 offset:256
	ds_read_b128 v[184:187], v149 offset:1280
	s_mov_b32 m0, s41
	ds_read_b128 v[140:143], v128 offset:32768
	ds_read_b128 v[188:191], v128 offset:33792
	ds_read_b128 v[192:195], v153 offset:32768
	ds_read_b128 v[196:199], v153 offset:33792
	ds_read_b128 v[200:203], v154 offset:32768
	ds_read_b128 v[204:207], v154 offset:33792
	ds_read_b128 v[208:211], v155 offset:32768
	ds_read_b128 v[212:215], v155 offset:33792
	global_load_lds_dwordx4 v[236:237], off
	s_mov_b32 m0, vcc_lo
	v_lshl_add_u64 v[132:133], v[236:237], 0, s[8:9]
	global_load_lds_dwordx4 v[238:239], off
	v_lshl_add_u64 v[134:135], v[238:239], 0, s[8:9]
	s_waitcnt lgkmcnt(8)
	s_barrier
	s_waitcnt lgkmcnt(0)
	s_setprio 1
	s_waitcnt lgkmcnt(0)
	v_mfma_f32_16x16x32_bf16 v[124:127], v[144:147], v[140:143], v[124:127]
	v_mfma_f32_16x16x32_bf16 v[120:123], v[180:183], v[140:143], v[120:123]
	v_mfma_f32_16x16x32_bf16 v[116:119], v[144:147], v[192:195], v[116:119]
	v_mfma_f32_16x16x32_bf16 v[112:115], v[180:183], v[192:195], v[112:115]
	v_mfma_f32_16x16x32_bf16 v[108:111], v[144:147], v[200:203], v[108:111]
	v_mfma_f32_16x16x32_bf16 v[104:107], v[180:183], v[200:203], v[104:107]
	v_mfma_f32_16x16x32_bf16 v[100:103], v[144:147], v[208:211], v[100:103]
	v_mfma_f32_16x16x32_bf16 v[96:99], v[180:183], v[208:211], v[96:99]
	v_mfma_f32_16x16x32_bf16 v[124:127], v[156:159], v[188:191], v[124:127]
	v_mfma_f32_16x16x32_bf16 v[120:123], v[184:187], v[188:191], v[120:123]
	v_mfma_f32_16x16x32_bf16 v[116:119], v[156:159], v[196:199], v[116:119]
	v_mfma_f32_16x16x32_bf16 v[112:115], v[184:187], v[196:199], v[112:115]
	v_mfma_f32_16x16x32_bf16 v[108:111], v[156:159], v[204:207], v[108:111]
	v_mfma_f32_16x16x32_bf16 v[104:107], v[184:187], v[204:207], v[104:107]
	v_mfma_f32_16x16x32_bf16 v[100:103], v[156:159], v[212:215], v[100:103]
	v_mfma_f32_16x16x32_bf16 v[96:99], v[184:187], v[212:215], v[96:99]
	s_setprio 0
	s_barrier
	s_mov_b32 m0, vcc_hi
	ds_read_b128 v[216:219], v148
	ds_read_b128 v[220:223], v148 offset:1024
	ds_read_b128 v[224:227], v148 offset:256
	ds_read_b128 v[228:231], v148 offset:1280
	global_load_lds_dwordx4 v[240:241], off
	s_mov_b32 m0, s28
	v_lshl_add_u64 v[136:137], v[240:241], 0, s[8:9]
	global_load_lds_dwordx4 v[242:243], off
	v_lshl_add_u64 v[138:139], v[242:243], 0, s[8:9]
	s_barrier
	s_waitcnt lgkmcnt(0)
	s_setprio 1
	s_waitcnt lgkmcnt(0)
	v_mfma_f32_16x16x32_bf16 v[84:87], v[216:219], v[140:143], v[84:87]
	v_mfma_f32_16x16x32_bf16 v[68:71], v[224:227], v[140:143], v[68:71]
	v_mfma_f32_16x16x32_bf16 v[52:55], v[216:219], v[192:195], v[52:55]
	v_mfma_f32_16x16x32_bf16 v[48:51], v[224:227], v[192:195], v[48:51]
	v_mfma_f32_16x16x32_bf16 v[44:47], v[216:219], v[200:203], v[44:47]
	v_mfma_f32_16x16x32_bf16 v[40:43], v[224:227], v[200:203], v[40:43]
	v_mfma_f32_16x16x32_bf16 v[36:39], v[216:219], v[208:211], v[36:39]
	v_mfma_f32_16x16x32_bf16 v[32:35], v[224:227], v[208:211], v[32:35]
	v_mfma_f32_16x16x32_bf16 v[84:87], v[220:223], v[188:191], v[84:87]
	v_mfma_f32_16x16x32_bf16 v[68:71], v[228:231], v[188:191], v[68:71]
	v_mfma_f32_16x16x32_bf16 v[52:55], v[220:223], v[196:199], v[52:55]
	v_mfma_f32_16x16x32_bf16 v[48:51], v[228:231], v[196:199], v[48:51]
	v_mfma_f32_16x16x32_bf16 v[44:47], v[220:223], v[204:207], v[44:47]
	v_mfma_f32_16x16x32_bf16 v[40:43], v[228:231], v[204:207], v[40:43]
	v_mfma_f32_16x16x32_bf16 v[36:39], v[220:223], v[212:215], v[36:39]
	v_mfma_f32_16x16x32_bf16 v[32:35], v[228:231], v[212:215], v[32:35]
	s_setprio 0
	s_mov_b32 m0, s94
	s_barrier
; #define STAGE(P, q) do { GLDS16(q[0], (unsigned char*)(P) + wid * 1024); GLDS16(q[1], (unsigned char*)(P) + wid * 1024 + 8192); \
;     q[0] += 128; q[1] += 128; asm volatile("" : "+v"(q[0]), "+v"(q[1])); } while (0)
; #define LDA(dst, b, h) _Pragma("unroll") for (int m = 0; m < 4; ++m) _Pragma("unroll") for (int k = 0; k < 2; ++k) \
;     dst[m][k] = *(const bf16x8*)((const unsigned char*)SA(b, h) + lds_byte1(wr * 64 + m * 16 + fr, k * 32 + fq * 8))
; #define LDB(dst, b, h) _Pragma("unroll") for (int n = 0; n < 2; ++n) _Pragma("unroll") for (int k = 0; k < 2; ++k) \
;     dst[n][k] = *(const bf16x8*)((const unsigned char*)SB(b, h) + lds_byte1(wc * 32 + n * 16 + fr, k * 32 + fq * 8))
; #define MMA(ai, bj, At_, Bt_) do { __builtin_amdgcn_s_setprio(1); \
;     _Pragma("unroll") for (int m = 0; m < 4; ++m) _Pragma("unroll") for (int n = 0; n < 2; ++n) _Pragma("unroll") for (int k = 0; k < 2; ++k) \
;       acc[ai][bj][m][n] = mfma16(At_[m][k], Bt_[n][k], acc[ai][bj][m][n]); \
;     __builtin_amdgcn_s_setprio(0); } while (0)
; #define WAIT_V(n) asm volatile("s_waitcnt vmcnt(" #n ")" ::: "memory")
; #define WAIT_L(n) asm volatile("s_waitcnt lgkmcnt(" #n ")" ::: "memory")
; #define BAR __builtin_amdgcn_s_barrier()
; #define SCHED __builtin_amdgcn_sched_barrier(0)
; DEV void gemm_tile(const u16* __restrict__ A, const u16* __restrict__ Bt, u16* __restrict__ C, int N, int K,
;                    int brow, int bcol, unsigned char* smem, int epi, const GateEpi& ge) {
;     ...
;     BAR; WAIT_L(0); MMA(1, 0, At, B0); BAR; SCHED;
;     STAGE(SB(1, 1), qB1);
;     WAIT_V(6); BAR; MMA(1, 1, At, B1); BAR;
;   }
;   { LDB(B0, 0, 0); LDA(At, 0, 0); STAGE(SA(1, 1), qA1);
;     BAR; WAIT_L(0); MMA(0, 0, At, B0); BAR;
;     LDB(B1, 0, 1); BAR; WAIT_L(0); MMA(0, 1, At, B1); BAR;
;     LDA(At, 0, 1); WAIT_V(4); BAR; WAIT_L(0); MMA(1, 0, At, B0); MMA(1, 1, At, B1); BAR; }
;   { LDB(B0, 1, 0); LDA(At, 1, 0); WAIT_V(2); BAR; WAIT_L(0); MMA(0, 0, At, B0); BAR;
;     ...
;     for (int n = 0; n < 2; ++n) {
;       const int cg = pn * 128 + wc * 32 + n * 16 + fr2;
;       w0[n] = ge.cw[cg]; w1[n] = ge.cw[DFF + cg]; w2[n] = ge.cw[2 * DFF + cg]; bs[n] = ge.cb[cg];
;     }
	ds_read_b128 v[188:191], v128 offset:49152
	ds_read_b128 v[192:195], v128 offset:50176
	ds_read_b128 v[196:199], v153 offset:49152
	ds_read_b128 v[200:203], v153 offset:50176
	ds_read_b128 v[204:207], v154 offset:49152
	ds_read_b128 v[208:211], v154 offset:50176
	ds_read_b128 v[212:215], v155 offset:49152
	ds_read_b128 v[232:235], v155 offset:50176
	global_load_lds_dwordx4 v[244:245], off
	s_mov_b32 m0, s95
	v_lshl_add_u64 v[140:141], v[244:245], 0, s[8:9]
	global_load_lds_dwordx4 v[246:247], off
	v_lshl_add_u64 v[142:143], v[246:247], 0, s[8:9]
	s_barrier
	s_waitcnt lgkmcnt(0)
	s_setprio 1
	s_waitcnt lgkmcnt(0)
	v_mfma_f32_16x16x32_bf16 v[28:31], v[144:147], v[188:191], v[28:31]
	v_mfma_f32_16x16x32_bf16 v[24:27], v[180:183], v[188:191], v[24:27]
	v_mfma_f32_16x16x32_bf16 v[20:23], v[144:147], v[196:199], v[20:23]
	v_mfma_f32_16x16x32_bf16 v[16:19], v[180:183], v[196:199], v[16:19]
	v_mfma_f32_16x16x32_bf16 v[12:15], v[144:147], v[204:207], v[12:15]
	v_mfma_f32_16x16x32_bf16 v[8:11], v[180:183], v[204:207], v[8:11]
	v_mfma_f32_16x16x32_bf16 v[4:7], v[144:147], v[212:215], v[4:7]
	v_mfma_f32_16x16x32_bf16 v[0:3], v[180:183], v[212:215], v[0:3]
	v_mfma_f32_16x16x32_bf16 v[28:31], v[156:159], v[192:195], v[28:31]
	v_mfma_f32_16x16x32_bf16 v[24:27], v[184:187], v[192:195], v[24:27]
	v_mfma_f32_16x16x32_bf16 v[20:23], v[156:159], v[200:203], v[20:23]
	v_mfma_f32_16x16x32_bf16 v[16:19], v[184:187], v[200:203], v[16:19]
	v_mfma_f32_16x16x32_bf16 v[12:15], v[156:159], v[208:211], v[12:15]
	v_mfma_f32_16x16x32_bf16 v[8:11], v[184:187], v[208:211], v[8:11]
	v_mfma_f32_16x16x32_bf16 v[4:7], v[156:159], v[232:235], v[4:7]
	v_mfma_f32_16x16x32_bf16 v[0:3], v[184:187], v[232:235], v[0:3]
	s_setprio 0
	s_barrier
	s_mov_b32 m0, s62
	v_lshl_add_u64 v[144:145], v[248:249], 0, s[8:9]
	global_load_lds_dwordx4 v[248:249], off
	s_mov_b32 m0, s63
	v_lshl_add_u64 v[146:147], v[250:251], 0, s[8:9]
	global_load_lds_dwordx4 v[250:251], off
	s_waitcnt vmcnt(6)
	s_barrier
	s_setprio 1
	v_mfma_f32_16x16x32_bf16 v[56:59], v[216:219], v[188:191], v[56:59]
	v_mfma_f32_16x16x32_bf16 v[60:63], v[224:227], v[188:191], v[60:63]
	v_mfma_f32_16x16x32_bf16 v[64:67], v[216:219], v[196:199], v[64:67]
	v_mfma_f32_16x16x32_bf16 v[72:75], v[224:227], v[196:199], v[72:75]
	v_mfma_f32_16x16x32_bf16 v[76:79], v[216:219], v[204:207], v[76:79]
	v_mfma_f32_16x16x32_bf16 v[80:83], v[224:227], v[204:207], v[80:83]
	v_mfma_f32_16x16x32_bf16 v[88:91], v[216:219], v[212:215], v[88:91]
	v_mfma_f32_16x16x32_bf16 v[92:95], v[224:227], v[212:215], v[92:95]
	v_mfma_f32_16x16x32_bf16 v[56:59], v[220:223], v[192:195], v[56:59]
	v_mfma_f32_16x16x32_bf16 v[60:63], v[228:231], v[192:195], v[60:63]
	v_mfma_f32_16x16x32_bf16 v[64:67], v[220:223], v[200:203], v[64:67]
	v_mfma_f32_16x16x32_bf16 v[72:75], v[228:231], v[200:203], v[72:75]
	v_mfma_f32_16x16x32_bf16 v[76:79], v[220:223], v[208:211], v[76:79]
	v_mfma_f32_16x16x32_bf16 v[80:83], v[228:231], v[208:211], v[80:83]
	v_mfma_f32_16x16x32_bf16 v[88:91], v[220:223], v[232:235], v[88:91]
	v_mfma_f32_16x16x32_bf16 v[92:95], v[228:231], v[232:235], v[92:95]
	s_setprio 0
	s_add_i32 s57, s57, 2
	s_cmp_lt_i32 s57, s45
	s_barrier
	s_cbranch_scc1 .LBB0_634
	s_add_i32 s0, s48, s33
	s_cmp_lt_i32 s0, s43
	s_cbranch_scc1 .Lg_last
	ds_read_b128 v[156:159], v152
	ds_read_b128 v[180:183], v152 offset:1024
	ds_read_b128 v[184:187], v152 offset:256
	ds_read_b128 v[188:191], v152 offset:1280
	s_mov_b32 m0, s56
	v_add_u32_e32 v153, s53, v151
	v_add_u32_e32 v154, s54, v151
	v_add_u32_e32 v155, s55, v151
	ds_read_b128 v[192:195], v128
	ds_read_b128 v[196:199], v128 offset:1024
	ds_read_b128 v[200:203], v153
	ds_read_b128 v[204:207], v153 offset:1024
	ds_read_b128 v[208:211], v154
	ds_read_b128 v[212:215], v154 offset:1024
	ds_read_b128 v[216:219], v155
	ds_read_b128 v[220:223], v155 offset:1024
	global_load_lds_dwordx4 v[132:133], off
	s_mov_b32 m0, s52
	v_lshl_add_u64 v[236:237], v[132:133], 0, s[8:9]
	global_load_lds_dwordx4 v[134:135], off
	v_lshl_add_u64 v[238:239], v[134:135], 0, s[8:9]
	s_andn2_b64 s[54:55], exec, s[2:3]
	s_cmp_lg_u64 s[54:55], 0
	s_cbranch_scc1 .Lwdma_skip_drain
	v_readlane_b32 s54, v252, 38
	v_readlane_b32 s55, v252, 39
	v_readlane_b32 s58, v252, 40
	v_readlane_b32 s59, v252, 41
	s_lshl_b32 s0, s92, 1
	s_lshl_b32 s53, s50, 7
	s_add_i32 s0, s0, s53
	v_mbcnt_lo_u32_b32 v224, -1, 0
	v_mbcnt_hi_u32_b32 v224, -1, v224
	v_and_b32_e32 v230, 7, v224
	v_lshlrev_b32_e32 v230, 4, v230
	v_add_u32_e32 v230, s0, v230
	v_bfe_u32 v226, v224, 3, 2
	v_mul_u32_u24_e32 v228, 0x5800, v226
	v_add_u32_e32 v228, v228, v230
	v_mov_b32_e32 v229, 0
	v_mov_b32_e32 v231, 0
	v_lshl_add_u64 v[232:233], s[54:55], 0, v[228:229]
	v_lshl_add_u64 v[234:235], s[58:59], 0, v[230:231]
	v_cmp_eq_u32_e64 s[54:55], 3, v226
	s_add_i32 s0, s1, 0x21000
	s_mov_b32 m0, s0
	v_cndmask_b32_e64 v232, v232, v234, s[54:55]
	v_cndmask_b32_e64 v233, v233, v235, s[54:55]
	s_nop 1
	global_load_lds_dwordx4 v[232:233], off

; DEV void gemm_tile(const u16* __restrict__ A, const u16* __restrict__ Bt, u16* __restrict__ C, int N, int K,
;                    int brow, int bcol, unsigned char* smem, int epi, const GateEpi& ge) {
;     ...
;     for (int n = 0; n < 2; ++n) {
;       const int cg = pn * 128 + wc * 32 + n * 16 + fr2;
;       w0[n] = ge.cw[cg]; w1[n] = ge.cw[DFF + cg]; w2[n] = ge.cw[2 * DFF + cg]; bs[n] = ge.cb[cg];
;     }
; DEV void phase_gemm(const u16* A, const u16* Bt, u16* C, int ntiles, int N, int K, unsigned char* smem, int epi, const GateEpi& ge) {
;     ...
;   for (int t = lb; t < ntiles; t += gridDim.x) {
;     while (rem >= nig) { rem -= nig; ++gid; }
;     const int pm = gid * 8 + (rem & 7), pn = rem >> 3;
;     gemm_tile(A, Bt, C, N, K, pm * 256, pn * 256, smem, epi, ge);
.Lg_normdone:
	v_writelane_b32 v252, s0, 42
	v_writelane_b32 v252, s58, 43
	s_lshl_b32 s54, s58, 12
	s_lshr_b32 s55, s0, 5
	s_and_b32 s55, s55, 1
	s_lshl_b32 s55, s55, 11
	s_or_b32 s54, s54, s55
	s_and_b32 s55, s0, 7
	s_lshl_b32 s55, s55, 8
	s_or_b32 s59, s54, s55
	s_lshr_b32 s54, s0, 6
	s_lshl_b32 s54, s54, 2
	s_bfe_u32 s55, s0, 0x20003
	s_or_b32 s54, s54, s55
	s_lshl_b32 s53, s54, 8
	s_sub_i32 s59, s59, s49
	s_add_i32 s59, s59, -1
	s_sub_i32 s53, s53, s92
	s_add_i32 s53, s53, -1
	s_lshl_b32 s0, s18, 1
	s_mul_hi_i32 s55, s59, s0
	s_mul_i32 s54, s59, s0
	v_lshl_add_u64 v[140:141], v[140:141], 0, s[54:55]
	v_lshl_add_u64 v[142:143], v[142:143], 0, s[54:55]
	v_lshl_add_u64 v[236:237], v[236:237], 0, s[54:55]
	v_lshl_add_u64 v[238:239], v[238:239], 0, s[54:55]
	s_mul_hi_i32 s55, s53, s0
	s_mul_i32 s54, s53, s0
	v_lshl_add_u64 v[136:137], v[136:137], 0, s[54:55]
	v_lshl_add_u64 v[138:139], v[138:139], 0, s[54:55]
	v_lshl_add_u64 v[144:145], v[144:145], 0, s[54:55]
	v_lshl_add_u64 v[146:147], v[146:147], 0, s[54:55]
	s_andn2_b64 s[54:55], exec, s[2:3]
	s_cmp_lg_u64 s[54:55], 0
	s_cbranch_scc1 .Lwdma_skip_last
	v_readlane_b32 s54, v252, 38
	v_readlane_b32 s55, v252, 39
	v_readlane_b32 s58, v252, 40
	v_readlane_b32 s59, v252, 41
	s_lshl_b32 s0, s92, 1
	s_lshl_b32 s53, s50, 7
	s_add_i32 s0, s0, s53
	v_mbcnt_lo_u32_b32 v224, -1, 0
	v_mbcnt_hi_u32_b32 v224, -1, v224
	v_and_b32_e32 v230, 7, v224
	v_lshlrev_b32_e32 v230, 4, v230
	v_add_u32_e32 v230, s0, v230
	v_bfe_u32 v226, v224, 3, 2
	v_mul_u32_u24_e32 v228, 0x5800, v226
	v_add_u32_e32 v228, v228, v230
	v_mov_b32_e32 v229, 0
	v_mov_b32_e32 v231, 0
	v_lshl_add_u64 v[232:233], s[54:55], 0, v[228:229]
	v_lshl_add_u64 v[234:235], s[58:59], 0, v[230:231]
	v_cmp_eq_u32_e64 s[54:55], 3, v226
	s_add_i32 s0, s1, 0x21000
	s_mov_b32 m0, s0
	v_cndmask_b32_e64 v232, v232, v234, s[54:55]
	v_cndmask_b32_e64 v233, v233, v235, s[54:55]
	s_nop 1
	global_load_lds_dwordx4 v[232:233], off

; DEV float bf2f(u16 h) { return __uint_as_float(((uint32_t)h) << 16); }
; DEV void gemm_tile(const u16* __restrict__ A, const u16* __restrict__ Bt, u16* __restrict__ C, int N, int K,
;                    int brow, int bcol, unsigned char* smem, int epi, const GateEpi& ge) {
;     ...
;     const int pm = brow >> 8, pn = bcol >> 8;
;     float w0[2], w1[2], w2[2], bs[2];
; #pragma unroll
;     for (int n = 0; n < 2; ++n) {
;       const int cg = pn * 128 + wc * 32 + n * 16 + fr2;
;       w0[n] = ge.cw[cg]; w1[n] = ge.cw[DFF + cg]; w2[n] = ge.cw[2 * DFF + cg]; bs[n] = ge.cb[cg];
;     }
;     ...
;         const int R0 = ai * 128 + wr * 64 + m * 16 + fq2 * 4;
; #pragma unroll
;         for (int n = 0; n < 2; ++n) {
;           const int cl = wc * 32 + n * 16 + fr2, cg = pn * 128 + cl;
;           float am2 = 0.f, am1 = 0.f;
;           if (R0 > 0) { am2 = bf2f(sAt[(R0 - 2) * AS + cl]); am1 = bf2f(sAt[(R0 - 1) * AS + cl]); }
.Lg_gate:
	s_add_i32 s62, s1, 0x21000
	v_lshlrev_b32_e32 v154, 5, v181
	v_add_u32_e32 v154, s62, v154
	ds_read_b128 v[184:187], v154 offset:0
	ds_read_b128 v[188:191], v154 offset:16
	ds_read_b128 v[192:195], v154 offset:128
	ds_read_b128 v[196:199], v154 offset:144
	ds_read_b128 v[200:203], v154 offset:256
	ds_read_b128 v[204:207], v154 offset:272
	ds_read_b128 v[208:211], v154 offset:384
	ds_read_b128 v[212:215], v154 offset:400
	s_mov_b32 s0, s92
	s_lshl_b32 s1, s50, 6
	s_add_i32 s28, s0, s1
	s_add_i32 s0, s51, s49
	s_mul_hi_u32 s1, s0, s85
	s_mul_i32 s0, s0, s85
	s_add_u32 s0, s0, s28
	s_addc_u32 s1, s1, 0
	s_add_u32 s0, s80, s0
	s_addc_u32 s1, s81, s1
	s_ashr_i32 s4, s49, 8
	s_mul_i32 s4, s4, 0x5800
	s_add_i32 s4, s4, s28
	s_add_u32 s6, s22, s4
	s_addc_u32 s7, s23, 0
	s_add_u32 s54, s82, s4
	s_addc_u32 s55, s83, 0
	s_sub_u32 s54, s54, 0x26800
	s_subb_u32 s55, s55, 0
	s_add_u32 s4, s20, s4
	s_addc_u32 s5, s21, 0
	v_mul_u32_u24_e32 v153, 0x2c00, v180
	v_lshl_add_u32 v153, v181, 4, v153
	v_and_b32_e32 v157, 1, v180
	v_lshlrev_b32_e32 v157, 5, v157
	v_lshl_add_u32 v157, v181, 6, v157
	s_lshl_b32 s62, s50, 8
	s_add_i32 s62, s62, 0x20000
	v_add_u32_e32 v157, s62, v157
	s_lshl_b32 s62, s34, 10
	v_add_u32_e32 v158, s62, v157
	s_add_i32 s62, s34, 3
	s_and_b32 s62, s62, 3
	s_lshl_b32 s62, s62, 10
	v_add_u32_e32 v159, s62, v157
	s_mov_b32 s52, 0xbdd2d3e8
	s_mov_b32 s53, 0xbdd2d3e8
	s_mov_b32 s94, 1.0
	s_mov_b32 s95, 1.0
	s_mov_b32 exec_lo, 0xc000c000
	s_mov_b32 exec_hi, 0xc000c000
	ds_write_b128 v158, v[100:103]
	ds_write_b128 v158, v[96:99] offset:16
	ds_write_b128 v158, v[4:7] offset:2048
	ds_write_b128 v158, v[0:3] offset:2064
	s_mov_b64 exec, -1
	s_waitcnt lgkmcnt(0)
	s_barrier
; DEV float bf2f(u16 h) { return __uint_as_float(((uint32_t)h) << 16); }
; DEV void gemm_tile(const u16* __restrict__ A, const u16* __restrict__ Bt, u16* __restrict__ C, int N, int K,
;                    int brow, int bcol, unsigned char* smem, int epi, const GateEpi& ge) {
;     ...
; #pragma unroll
;     for (int ai = 0; ai < 2; ++ai)
; #pragma unroll
;       for (int m = 0; m < 4; ++m) {
;         const int R0 = ai * 128 + wr * 64 + m * 16 + fq2 * 4;
; #pragma unroll
;         for (int n = 0; n < 2; ++n) {
;           const int cl = wc * 32 + n * 16 + fr2, cg = pn * 128 + cl;
;           float am2 = 0.f, am1 = 0.f;
;           if (R0 > 0) { am2 = bf2f(sAt[(R0 - 2) * AS + cl]); am1 = bf2f(sAt[(R0 - 1) * AS + cl]); }
; #pragma unroll
;           for (int j = 0; j < 4; ++j) {
;             const float a0 = acc[ai][0][m][n][j], b0 = acc[ai][1][m][n][j];
;             if (R0 > 0 || j >= 2) {
;               const float gv = gelu_tanh(bs[n] + w0[n] * am2 + w1[n] * am1 + w2[n] * a0) * b0;
;               ge.g[(size_t)(brow + R0 + j) * DFF + cg] = f2bf(gv);
;             } else {
;               ge.first_a[((size_t)pm * 2 + j) * DFF + cg] = sAt[(R0 + j) * AS + cl];
;               ge.first_b[((size_t)pm * 2 + j) * DFF + cg] = f2bf(b0);
;             }
;             if (R0 == 252 && j >= 2) ge.halo_a[((size_t)pm * 2 + (j - 2)) * DFF + cg] = sAt[(R0 + j) * AS + cl];
;             am2 = am1; am1 = a0;
	ds_read_b128 v[232:235], v159
	ds_read_b128 v[236:239], v159 offset:16
	s_add_i32 s62, s34, 1
	s_lshl_b32 s62, s62, 10
	v_add_u32_e32 v156, s62, v157
	v_cmp_eq_u32_e32 vcc, 0, v180
	s_nop 1
	v_cndmask_b32_e32 v216, 0, v192, vcc
	v_cndmask_b32_e32 v217, 0, v193, vcc
	v_cndmask_b32_e32 v218, 0, v194, vcc
	v_cndmask_b32_e32 v219, 0, v195, vcc
	v_cndmask_b32_e32 v220, 0, v196, vcc
	v_cndmask_b32_e32 v221, 0, v197, vcc
	v_cndmask_b32_e32 v222, 0, v198, vcc
	v_cndmask_b32_e32 v223, 0, v199, vcc
	v_cmp_gt_u32_e32 vcc, 2, v180
	s_nop 1
	v_cndmask_b32_e32 v224, 0, v184, vcc
	v_cndmask_b32_e32 v225, 0, v185, vcc
	v_cndmask_b32_e32 v226, 0, v186, vcc
	v_cndmask_b32_e32 v227, 0, v187, vcc
	v_cndmask_b32_e32 v228, 0, v188, vcc
	v_cndmask_b32_e32 v229, 0, v189, vcc
	v_cndmask_b32_e32 v230, 0, v190, vcc
	v_cndmask_b32_e32 v231, 0, v191, vcc
	v_mov_b32_e32 v180, v163
	v_mov_b32_e32 v181, v163
	s_waitcnt lgkmcnt(0)
	v_pk_fma_f32 v[240:241], v[200:201], v[124:125], v[208:209]
	v_pk_fma_f32 v[242:243], v[202:203], v[126:127], v[210:211]
	v_pk_fma_f32 v[244:245], v[204:205], v[120:121], v[212:213]
	v_pk_fma_f32 v[246:247], v[206:207], v[122:123], v[214:215]
	v_fmac_f32_dpp v240, v124, v192 row_shr:1 row_mask:0xf bank_mask:0xf
	v_fmac_f32_dpp v241, v125, v193 row_shr:1 row_mask:0xf bank_mask:0xf
	v_fmac_f32_dpp v242, v126, v194 row_shr:1 row_mask:0xf bank_mask:0xf
	v_fmac_f32_dpp v243, v127, v195 row_shr:1 row_mask:0xf bank_mask:0xf
	v_fmac_f32_dpp v244, v120, v196 row_shr:1 row_mask:0xf bank_mask:0xf
	v_fmac_f32_dpp v245, v121, v197 row_shr:1 row_mask:0xf bank_mask:0xf
	v_fmac_f32_dpp v246, v122, v198 row_shr:1 row_mask:0xf bank_mask:0xf
	v_fmac_f32_dpp v247, v123, v199 row_shr:1 row_mask:0xf bank_mask:0xf
	v_fmac_f32_dpp v240, v232, v216 row_ror:1 row_mask:0xf bank_mask:0xf
	v_fmac_f32_dpp v241, v233, v217 row_ror:1 row_mask:0xf bank_mask:0xf
	v_fmac_f32_dpp v242, v234, v218 row_ror:1 row_mask:0xf bank_mask:0xf
	v_fmac_f32_dpp v243, v235, v219 row_ror:1 row_mask:0xf bank_mask:0xf
	v_fmac_f32_dpp v244, v236, v220 row_ror:1 row_mask:0xf bank_mask:0xf
	v_fmac_f32_dpp v245, v237, v221 row_ror:1 row_mask:0xf bank_mask:0xf
	v_fmac_f32_dpp v246, v238, v222 row_ror:1 row_mask:0xf bank_mask:0xf
	v_fmac_f32_dpp v247, v239, v223 row_ror:1 row_mask:0xf bank_mask:0xf
	v_fmac_f32_dpp v240, v124, v184 row_shr:2 row_mask:0xf bank_mask:0xf
	v_fmac_f32_dpp v241, v125, v185 row_shr:2 row_mask:0xf bank_mask:0xf
	v_fmac_f32_dpp v242, v126, v186 row_shr:2 row_mask:0xf bank_mask:0xf
	v_fmac_f32_dpp v243, v127, v187 row_shr:2 row_mask:0xf bank_mask:0xf
	v_fmac_f32_dpp v244, v120, v188 row_shr:2 row_mask:0xf bank_mask:0xf
	v_fmac_f32_dpp v245, v121, v189 row_shr:2 row_mask:0xf bank_mask:0xf
	v_fmac_f32_dpp v246, v122, v190 row_shr:2 row_mask:0xf bank_mask:0xf
	v_fmac_f32_dpp v247, v123, v191 row_shr:2 row_mask:0xf bank_mask:0xf
	v_fmac_f32_dpp v240, v232, v224 row_ror:2 row_mask:0xf bank_mask:0xf
	v_fmac_f32_dpp v241, v233, v225 row_ror:2 row_mask:0xf bank_mask:0xf
	v_fmac_f32_dpp v242, v234, v226 row_ror:2 row_mask:0xf bank_mask:0xf
	v_fmac_f32_dpp v243, v235, v227 row_ror:2 row_mask:0xf bank_mask:0xf
	v_fmac_f32_dpp v244, v236, v228 row_ror:2 row_mask:0xf bank_mask:0xf
	v_fmac_f32_dpp v245, v237, v229 row_ror:2 row_mask:0xf bank_mask:0xf
	v_fmac_f32_dpp v246, v238, v230 row_ror:2 row_mask:0xf bank_mask:0xf
	v_fmac_f32_dpp v247, v239, v231 row_ror:2 row_mask:0xf bank_mask:0xf
	ds_read_b128 v[232:235], v156
	ds_read_b128 v[236:239], v156 offset:16
	v_pk_mul_f32 v[248:249], v[240:241], v[240:241]
	v_pk_mul_f32 v[250:251], v[242:243], v[242:243]
	v_pk_mul_f32 v[182:183], v[244:245], v[244:245]
	v_pk_mul_f32 v[154:155], v[246:247], v[246:247]
	v_pk_fma_f32 v[248:249], v[248:249], s[52:53], v[180:181]
	v_pk_fma_f32 v[250:251], v[250:251], s[52:53], v[180:181]
	v_pk_fma_f32 v[182:183], v[182:183], s[52:53], v[180:181]
	v_pk_fma_f32 v[154:155], v[154:155], s[52:53], v[180:181]
	v_pk_mul_f32 v[248:249], v[240:241], v[248:249]
	v_pk_mul_f32 v[250:251], v[242:243], v[250:251]
	v_pk_mul_f32 v[182:183], v[244:245], v[182:183]
	v_pk_mul_f32 v[154:155], v[246:247], v[154:155]
	v_exp_f32_e32 v248, v248
	v_exp_f32_e32 v249, v249
	v_exp_f32_e32 v250, v250
	v_exp_f32_e32 v251, v251
	v_exp_f32_e32 v182, v182
	v_exp_f32_e32 v183, v183
	v_exp_f32_e32 v154, v154
	v_exp_f32_e32 v155, v155
	v_pk_add_f32 v[248:249], v[248:249], s[94:95]
	v_pk_add_f32 v[250:251], v[250:251], s[94:95]
	v_pk_add_f32 v[182:183], v[182:183], s[94:95]
	v_pk_add_f32 v[154:155], v[154:155], s[94:95]
	v_rcp_f32_e32 v248, v248
	v_rcp_f32_e32 v249, v249
	v_rcp_f32_e32 v250, v250
	v_rcp_f32_e32 v251, v251
	v_rcp_f32_e32 v182, v182
	v_rcp_f32_e32 v183, v183
	v_rcp_f32_e32 v154, v154
	v_rcp_f32_e32 v155, v155
	v_pk_mul_f32 v[240:241], v[240:241], v[248:249]
	v_pk_mul_f32 v[242:243], v[242:243], v[250:251]
	v_pk_mul_f32 v[244:245], v[244:245], v[182:183]
	v_pk_mul_f32 v[246:247], v[246:247], v[154:155]
	v_pk_mul_f32 v[240:241], v[240:241], v[84:85]
	v_pk_mul_f32 v[242:243], v[242:243], v[86:87]
	v_pk_mul_f32 v[244:245], v[244:245], v[68:69]
	v_pk_mul_f32 v[246:247], v[246:247], v[70:71]
	v_cvt_pk_bf16_f32 v248, v240, v241
	v_cvt_pk_bf16_f32 v249, v242, v243
	v_cvt_pk_bf16_f32 v250, v244, v245
	v_cvt_pk_bf16_f32 v251, v246, v247
	s_cmp_lg_u32 s34, 0
	s_cbranch_scc1 .Lgate_plain00_0
	s_mov_b32 exec_lo, 0x30003
	s_mov_b32 exec_hi, 0x30003
	v_cvt_pk_bf16_f32 v240, v124, v125
	v_cvt_pk_bf16_f32 v241, v126, v127
	v_cvt_pk_bf16_f32 v242, v120, v121
	v_cvt_pk_bf16_f32 v243, v122, v123
	v_cvt_pk_bf16_f32 v244, v84, v85
	v_cvt_pk_bf16_f32 v245, v86, v87
	v_cvt_pk_bf16_f32 v246, v68, v69
	v_cvt_pk_bf16_f32 v247, v70, v71
	global_store_dwordx4 v153, v[240:243], s[4:5]
	global_store_dwordx4 v153, v[244:247], s[6:7]
	s_not_b64 exec, exec
	global_store_dwordx4 v153, v[248:251], s[0:1]
	s_mov_b64 exec, -1
	s_branch .Lgate_done00_0

; #define STAGE(P, q) do { GLDS16(q[0], (unsigned char*)(P) + wid * 1024); GLDS16(q[1], (unsigned char*)(P) + wid * 1024 + 8192); \
;     q[0] += 128; q[1] += 128; asm volatile("" : "+v"(q[0]), "+v"(q[1])); } while (0)
; #define WAIT_V(n) asm volatile("s_waitcnt vmcnt(" #n ")" ::: "memory")
; #define BAR __builtin_amdgcn_s_barrier()
; DEV void gemm_tile(const u16* __restrict__ A, const u16* __restrict__ Bt, u16* __restrict__ C, int N, int K,
;                    int brow, int bcol, unsigned char* smem, int epi, const GateEpi& ge) {
;     ...
;   STAGE(SB(0, 0), qB0); STAGE(SA(0, 0), qA0);
;   STAGE(SB(0, 1), qB1); STAGE(SA(0, 1), qA1);
;   if (wr == 1) BAR;
;   WAIT_V(4); BAR;
;   STAGE(SB(1, 0), qB0); STAGE(SA(1, 0), qA0); STAGE(SB(1, 1), qB1);
;   WAIT_V(6); BAR;
; DEV void phase_gemm(const u16* A, const u16* Bt, u16* C, int ntiles, int N, int K, unsigned char* smem, int epi, const GateEpi& ge) {
;     ...
;   for (int t = lb; t < ntiles; t += gridDim.x) {
;     while (rem >= nig) { rem -= nig; ++gid; }
;     const int pm = gid * 8 + (rem & 7), pn = rem >> 3;
;     gemm_tile(A, Bt, C, N, K, pm * 256, pn * 256, smem, epi, ge);
;     rem += gridDim.x;
.Lgate_end_0:
.Lg_post:
	s_cmp_eq_u32 s63, 0
	s_cbranch_scc1 .LBB0_818
	s_add_i32 s48, s48, s33
	v_readlane_b32 s47, v252, 42
	v_readlane_b32 s46, v252, 43
	s_lshl_b32 s0, s46, 12
	s_lshr_b32 s1, s47, 5
	s_and_b32 s1, s1, 1
	s_lshl_b32 s1, s1, 11
	s_or_b32 s0, s0, s1
	s_and_b32 s1, s47, 7
	s_lshl_b32 s1, s1, 8
	s_or_b32 s49, s0, s1
	s_lshr_b32 s0, s47, 6
	s_lshl_b32 s0, s0, 2
	s_bfe_u32 s1, s47, 0x20003
	s_or_b32 s0, s0, s1
	s_lshl_b32 s92, s0, 8
	s_ashr_i32 s93, s92, 31
	s_lshl_b32 s1, s34, 2
	s_add_i32 s1, s1, s50
	s_lshl_b32 s1, s1, 10
	s_add_i32 s56, s1, 0xc000
	s_add_i32 s52, s1, 0xe000
	s_add_i32 s4, s1, 0x10000
	s_add_i32 s5, s1, 0x12000
	s_add_i32 s6, s1, 0x2000
	s_add_i32 s7, s1, 0x14000
	s_add_i32 s35, s1, 0x16000
	s_add_i32 s41, s1, 0x4000
	s_add_i32 vcc_lo, s1, 0x6000
	s_add_i32 vcc_hi, s1, 0x18000
	s_add_i32 s28, s1, 0x1a000
	s_add_i32 s94, s1, 0x8000
	s_add_i32 s95, s1, 0xa000
	s_add_i32 s62, s1, 0x1c000
	s_add_i32 s63, s1, 0x1e000
	s_lshl_b32 s59, s34, 13
	s_or_b32 s53, s59, 0x800
	s_or_b32 s54, s59, 0x1000
	s_or_b32 s55, s59, 0x1800
	s_mov_b32 s57, 2
	s_andn2_b64 s[58:59], exec, s[2:3]
	s_cmp_lg_u64 s[58:59], 0
	s_cbranch_scc1 .Lg_nostag
	s_cmp_lg_u32 s34, 1
	s_cbranch_scc1 .Lg_nostag
	s_barrier
